# P10 output stores write-through (sc0 sc1 instead of nt) to avoid a dirty-L2 flush at kernel end, on top of local-barrier-2 mid flush
# speedup vs baseline: 1.0042x; 1.0042x over previous
; __device__ __forceinline__ void p10_rows(const Params& P, LAS unsigned char* lds, int G) {
;     ...
;         const int b = m >> 13; const u32x2* fr = (const u32x2*)(F + (size_t)m * DM) + lane; f32x4* outr = (f32x4*)(P.out + (size_t)m * DM) + lane; const u32x2* x1r = (const u32x2*)((const bf16_t*)(P.ws + WS_X1) + (size_t)m * DM) + lane;
;         f32x4 v[8]; u32x2 xw8[8]; float ss = 0.f;
; #pragma unroll
;         for (int j = 0; j < 8; ++j) xw8[j] = __builtin_nontemporal_load(x1r + 64 * j);
; #pragma unroll
;         for (int j = 0; j < 8; ++j) { const u32x2 w = __builtin_nontemporal_load(fr + 64 * j); v[j][0] = __uint_as_float(w.x << 16); v[j][1] = __uint_as_float(w.x & 0xffff0000u); v[j][2] = __uint_as_float(w.y << 16); v[j][3] = __uint_as_float(w.y & 0xffff0000u);
;             ss += (v[j][0] * v[j][0] + v[j][1] * v[j][1]) + (v[j][2] * v[j][2] + v[j][3] * v[j][3]); }
.LBB0_1021:
	v_add_co_u32_e32 v22, vcc, 0xf0800000, v2
	global_load_dwordx2 v[20:21], v[2:3], off nt
	global_load_dwordx2 v[18:19], v[2:3], off offset:512 nt
	global_load_dwordx2 v[16:17], v[2:3], off offset:1024 nt
	global_load_dwordx2 v[14:15], v[2:3], off offset:1536 nt
	global_load_dwordx2 v[12:13], v[2:3], off offset:2048 nt
	global_load_dwordx2 v[10:11], v[2:3], off offset:2560 nt
	global_load_dwordx2 v[8:9], v[2:3], off offset:3072 nt
	global_load_dwordx2 v[6:7], v[2:3], off offset:3584 nt
	v_addc_co_u32_e32 v23, vcc, -1, v3, vcc
	v_and_b32_e32 v31, 0xffffe000, v0
	v_add_co_u32_e32 v64, vcc, s10, v2
	global_load_dwordx2 v[22:23], v[22:23], off nt
	v_add_u32_e32 v31, v30, v31
	v_addc_co_u32_e32 v65, vcc, -1, v3, vcc
	ds_read_b128 v[32:35], v31
	ds_read_b128 v[36:39], v31 offset:1024
	ds_read_b128 v[40:43], v31 offset:2048
	ds_read_b128 v[44:47], v31 offset:3072
	ds_read_b128 v[48:51], v31 offset:4096
	ds_read_b128 v[52:55], v31 offset:5120
	ds_read_b128 v[56:59], v31 offset:6144
	ds_read_b128 v[60:63], v31 offset:7168
	global_load_dwordx2 v[66:67], v[64:65], off offset:-3584 nt
	global_load_dwordx2 v[68:69], v[64:65], off offset:-3072 nt
	global_load_dwordx2 v[70:71], v[64:65], off offset:-2560 nt
	global_load_dwordx2 v[72:73], v[64:65], off offset:-2048 nt
	global_load_dwordx2 v[74:75], v[64:65], off offset:-1536 nt
	global_load_dwordx2 v[76:77], v[64:65], off offset:-1024 nt
	global_load_dwordx2 v[78:79], v[64:65], off offset:-512 nt
	v_add_u32_e32 v0, s42, v0
	v_cmp_lt_i32_e64 s[0:1], s12, v0
	v_lshl_add_u64 v[2:3], v[2:3], 0, s[4:5]
	s_or_b64 s[8:9], s[0:1], s[8:9]
	s_waitcnt vmcnt(15)
	v_lshlrev_b32_e32 v64, 16, v20
	v_and_b32_e32 v65, 0xffff0000, v20
	v_lshlrev_b32_e32 v20, 16, v21
	s_waitcnt vmcnt(12)
	v_lshlrev_b32_e32 v84, 16, v14
	v_and_b32_e32 v85, 0xffff0000, v14
	v_lshlrev_b32_e32 v86, 16, v15
	s_waitcnt vmcnt(9)
	v_lshlrev_b32_e32 v98, 16, v9
	v_and_b32_e32 v99, 0xffff0000, v9
	s_waitcnt vmcnt(8)
	v_lshlrev_b32_e32 v102, 16, v7
	v_and_b32_e32 v103, 0xffff0000, v7
	v_and_b32_e32 v87, 0xffff0000, v15
	v_lshlrev_b32_e32 v88, 16, v12
	v_and_b32_e32 v89, 0xffff0000, v12
	s_waitcnt vmcnt(7)
	v_and_b32_e32 v7, 0xffff0000, v22
	v_and_b32_e32 v9, 0xffff0000, v23
	v_lshlrev_b32_e32 v90, 16, v13
	v_and_b32_e32 v91, 0xffff0000, v13
	v_lshlrev_b32_e32 v92, 16, v10
	v_and_b32_e32 v93, 0xffff0000, v10
	v_lshlrev_b32_e32 v94, 16, v11
	v_and_b32_e32 v95, 0xffff0000, v11
	v_lshlrev_b32_e32 v96, 16, v8
	v_and_b32_e32 v97, 0xffff0000, v8
	v_lshlrev_b32_e32 v100, 16, v6
	v_and_b32_e32 v101, 0xffff0000, v6
	v_lshlrev_b32_e32 v6, 16, v22
	v_lshlrev_b32_e32 v8, 16, v23
	v_mul_f32_e32 v10, v9, v9
	s_waitcnt vmcnt(6)
	v_lshlrev_b32_e32 v13, 16, v67
	v_lshlrev_b32_e32 v12, 16, v66
	v_and_b32_e32 v15, 0xffff0000, v67
	v_and_b32_e32 v14, 0xffff0000, v66
	s_waitcnt vmcnt(5)
	v_lshlrev_b32_e32 v22, 16, v68
	v_and_b32_e32 v23, 0xffff0000, v68
	v_lshlrev_b32_e32 v66, 16, v69
	v_and_b32_e32 v67, 0xffff0000, v69
	s_waitcnt vmcnt(4)
	v_lshlrev_b32_e32 v11, 16, v70
	v_and_b32_e32 v69, 0xffff0000, v70
	v_mul_f32_e32 v68, v7, v7
	s_waitcnt vmcnt(0)
; #define LAS __attribute__((address_space(3)))
; __device__ __forceinline__ void p10_rows(const Params& P, LAS unsigned char* lds, int G) {
;     ...
;         for (int j = 0; j < 8; ++j) { const u32x2 w = __builtin_nontemporal_load(fr + 64 * j); v[j][0] = __uint_as_float(w.x << 16); v[j][1] = __uint_as_float(w.x & 0xffff0000u); v[j][2] = __uint_as_float(w.y << 16); v[j][3] = __uint_as_float(w.y & 0xffff0000u);
;             ss += (v[j][0] * v[j][0] + v[j][1] * v[j][1]) + (v[j][2] * v[j][2] + v[j][3] * v[j][3]); }
;         const float rstd = rsqrtf(wave_sum(ss) * (1.0f / DM) + RMS_EPS);
; #pragma unroll
;         for (int j = 0; j < 8; ++j) { const f32x4 a = *(const LAS f32x4*)(TA + b * DM + 256 * j + 4 * lane); const u32x2 xw = xw8[j]; f32x4 x1; x1[0] = __uint_as_float(xw.x << 16); x1[1] = __uint_as_float(xw.x & 0xffff0000u); x1[2] = __uint_as_float(xw.y << 16); x1[3] = __uint_as_float(xw.y & 0xffff0000u); __builtin_nontemporal_store(x1 + v[j] * rstd * a, outr + 64 * j); }
	v_lshlrev_b32_e32 v111, 16, v78
	v_pk_fma_f32 v[114:115], v[8:9], v[8:9], v[10:11] op_sel_hi:[1,1,0]
	v_pk_mul_f32 v[116:117], v[14:15], v[14:15]
	v_pk_fma_f32 v[118:119], v[6:7], v[6:7], v[68:69] op_sel_hi:[1,1,0]
	v_lshlrev_b32_e32 v70, 16, v71
	v_and_b32_e32 v71, 0xffff0000, v71
	v_mov_b32_e32 v121, v11
	v_mul_f32_e32 v110, v23, v23
	v_mul_f32_e32 v122, v67, v67
	v_mov_b32_e32 v123, v111
	v_mov_b32_e32 v132, v12
	v_mov_b32_e32 v133, v14
	v_mov_b32_e32 v14, v13
	v_pk_fma_f32 v[12:13], v[12:13], v[12:13], v[116:117]
	v_mov_b32_e32 v10, v118
	v_mov_b32_e32 v120, v114
	v_mul_f32_e32 v31, v69, v69
	v_mul_f32_e32 v129, v70, v70
	v_mul_f32_e32 v131, v71, v71
	v_mov_b32_e32 v68, v11
	v_pk_add_f32 v[114:115], v[118:119], v[114:115]
	v_pk_fma_f32 v[116:117], v[22:23], v[22:23], v[110:111] op_sel_hi:[1,1,0]
	v_pk_fma_f32 v[118:119], v[66:67], v[66:67], v[122:123] op_sel_hi:[1,1,0]
	v_pk_mul_f32 v[10:11], v[10:11], v[120:121]
	v_pk_add_f32 v[12:13], v[12:13], v[12:13] op_sel:[0,1] op_sel_hi:[1,0]
	v_lshlrev_b32_e32 v105, 16, v73
	v_lshlrev_b32_e32 v104, 16, v72
	v_and_b32_e32 v73, 0xffff0000, v73
	v_and_b32_e32 v72, 0xffff0000, v72
	v_mov_b32_e32 v117, v129
	v_mov_b32_e32 v119, v131
	v_mov_b32_e32 v115, v11
	v_mov_b32_e32 v13, v31
	v_pk_mul_f32 v[124:125], v[72:73], v[72:73]
	v_pk_add_f32 v[10:11], v[116:117], v[118:119]
	v_pk_add_f32 v[12:13], v[114:115], v[12:13]
	v_lshlrev_b32_e32 v107, 16, v75
	v_lshlrev_b32_e32 v106, 16, v74
	v_and_b32_e32 v75, 0xffff0000, v75
	v_and_b32_e32 v74, 0xffff0000, v74
	v_mov_b32_e32 v134, v104
	v_mov_b32_e32 v135, v72
	v_mov_b32_e32 v72, v105
	v_pk_fma_f32 v[104:105], v[104:105], v[104:105], v[124:125]
	v_pk_add_f32 v[10:11], v[12:13], v[10:11]
	v_lshlrev_b32_e32 v108, 16, v76
	v_and_b32_e32 v109, 0xffff0000, v76
	v_lshlrev_b32_e32 v76, 16, v77
	v_and_b32_e32 v77, 0xffff0000, v77
	v_pk_mul_f32 v[126:127], v[74:75], v[74:75]
	v_pk_add_f32 v[104:105], v[104:105], v[104:105] op_sel:[0,1] op_sel_hi:[1,0]
	v_pk_add_f32 v[10:11], v[10:11], v[10:11] op_sel:[0,1] op_sel_hi:[1,0]
	v_and_b32_e32 v113, 0xffff0000, v78
	v_lshlrev_b32_e32 v78, 16, v79
	v_and_b32_e32 v79, 0xffff0000, v79
	v_mul_f32_e32 v128, v109, v109
	v_mul_f32_e32 v130, v77, v77
	v_mov_b32_e32 v136, v106
	v_mov_b32_e32 v137, v74
	v_mov_b32_e32 v74, v107
	v_pk_fma_f32 v[106:107], v[106:107], v[106:107], v[126:127]
	v_mov_b32_e32 v122, v104
	v_mov_b32_e32 v110, v10
	v_mul_f32_e32 v138, v113, v113
	v_mul_f32_e32 v139, v78, v78
	v_mul_f32_e32 v140, v79, v79
	v_pk_fma_f32 v[124:125], v[108:109], v[108:109], v[128:129] op_sel_hi:[1,1,0]
	v_pk_fma_f32 v[126:127], v[76:77], v[76:77], v[130:131] op_sel_hi:[1,1,0]
	v_pk_add_f32 v[106:107], v[106:107], v[106:107] op_sel:[0,1] op_sel_hi:[1,0]
	v_pk_add_f32 v[10:11], v[10:11], v[104:105]
	v_pk_mul_f32 v[12:13], v[110:111], v[122:123]
	v_mov_b32_e32 v125, v139
	v_mov_b32_e32 v127, v140
	v_mov_b32_e32 v107, v138
	v_mov_b32_e32 v11, v13
	v_pk_add_f32 v[116:117], v[124:125], v[126:127]
	v_pk_add_f32 v[10:11], v[10:11], v[106:107]
	v_and_b32_e32 v21, 0xffff0000, v21
	v_pk_add_f32 v[10:11], v[10:11], v[116:117]
	v_mov_b32_e32 v112, v111
	v_add_f32_e32 v10, v10, v11
	s_nop 1
	v_add_f32_dpp v10, v10, v10 quad_perm:[1,0,3,2] row_mask:0xf bank_mask:0xf
	v_lshlrev_b32_e32 v80, 16, v18
	v_and_b32_e32 v81, 0xffff0000, v18
	v_lshlrev_b32_e32 v18, 16, v19
	v_and_b32_e32 v19, 0xffff0000, v19
	s_nop 1
	v_add_f32_dpp v10, v10, v10 quad_perm:[2,3,0,1] row_mask:0xf bank_mask:0xf
	v_lshlrev_b32_e32 v82, 16, v16
	v_and_b32_e32 v83, 0xffff0000, v16
	v_lshlrev_b32_e32 v16, 16, v17
	v_and_b32_e32 v17, 0xffff0000, v17
	s_nop 1
	v_add_f32_dpp v10, v10, v10 row_half_mirror row_mask:0xf bank_mask:0xf
	s_nop 1
	v_add_f32_dpp v10, v10, v10 row_mirror row_mask:0xf bank_mask:0xf
	v_mov_b32_e32 v11, v10
	s_nop 1
	v_permlane16_swap_b32_e32 v11, v10
	v_add_f32_e32 v10, v10, v11
	v_mov_b32_e32 v11, v10
	s_nop 1
	v_permlane32_swap_b32_e32 v11, v10
	v_add_f32_e32 v10, v10, v11
	s_waitcnt lgkmcnt(0)
	v_fmamk_f32 v10, v10, 0x3a000000, v1
	v_mul_f32_e32 v11, 0x4b800000, v10
	v_cmp_gt_f32_e32 vcc, s11, v10
	s_nop 1
	v_cndmask_b32_e32 v10, v10, v11, vcc
	v_rsq_f32_e32 v10, v10
	s_nop 0
	v_mul_f32_e32 v11, 0x45800000, v10
	v_cndmask_b32_e32 v10, v10, v11, vcc
	v_pk_mul_f32 v[6:7], v[10:11], v[6:7] op_sel_hi:[0,1]
	v_pk_mul_f32 v[8:9], v[10:11], v[8:9] op_sel_hi:[0,1]
	v_pk_mul_f32 v[104:105], v[10:11], v[132:133] op_sel_hi:[0,1]
	v_pk_mul_f32 v[12:13], v[10:11], v[14:15] op_sel_hi:[0,1]
	v_pk_mul_f32 v[14:15], v[10:11], v[22:23] op_sel_hi:[0,1]
	v_pk_mul_f32 v[22:23], v[10:11], v[66:67] op_sel_hi:[0,1]
	v_pk_mul_f32 v[66:67], v[68:69], v[10:11] op_sel_hi:[1,0]
	v_pk_mul_f32 v[68:69], v[70:71], v[10:11] op_sel_hi:[1,0]
	v_pk_mul_f32 v[70:71], v[10:11], v[134:135] op_sel_hi:[0,1]
	v_pk_mul_f32 v[72:73], v[10:11], v[72:73] op_sel_hi:[0,1]
	v_pk_mul_f32 v[106:107], v[10:11], v[136:137] op_sel_hi:[0,1]
	v_pk_mul_f32 v[74:75], v[10:11], v[74:75] op_sel_hi:[0,1]
	v_pk_mul_f32 v[108:109], v[10:11], v[108:109] op_sel_hi:[0,1]
	v_pk_mul_f32 v[76:77], v[10:11], v[76:77] op_sel_hi:[0,1]
	v_pk_mul_f32 v[110:111], v[112:113], v[10:11] op_sel_hi:[1,0]
	v_pk_mul_f32 v[78:79], v[78:79], v[10:11] op_sel_hi:[1,0]
	v_pk_fma_f32 v[8:9], v[34:35], v[8:9], v[20:21]
	v_pk_fma_f32 v[6:7], v[32:33], v[6:7], v[64:65]
	v_pk_fma_f32 v[12:13], v[38:39], v[12:13], v[18:19]
	v_pk_fma_f32 v[10:11], v[36:37], v[104:105], v[80:81]
	v_pk_fma_f32 v[16:17], v[42:43], v[22:23], v[16:17]
	v_pk_fma_f32 v[14:15], v[40:41], v[14:15], v[82:83]
	v_pk_fma_f32 v[20:21], v[46:47], v[68:69], v[86:87]
	v_pk_fma_f32 v[18:19], v[44:45], v[66:67], v[84:85]
	v_pk_fma_f32 v[34:35], v[50:51], v[72:73], v[90:91]
	v_pk_fma_f32 v[32:33], v[48:49], v[70:71], v[88:89]
	v_pk_fma_f32 v[38:39], v[54:55], v[74:75], v[94:95]
	v_pk_fma_f32 v[36:37], v[52:53], v[106:107], v[92:93]
	v_pk_fma_f32 v[42:43], v[58:59], v[76:77], v[98:99]
	v_pk_fma_f32 v[40:41], v[56:57], v[108:109], v[96:97]
	v_pk_fma_f32 v[46:47], v[62:63], v[78:79], v[102:103]
	v_pk_fma_f32 v[44:45], v[60:61], v[110:111], v[100:101]
	global_store_dwordx4 v[4:5], v[6:9], off offset:-4096 sc0 sc1
	global_store_dwordx4 v[4:5], v[10:13], off offset:-3072 sc0 sc1
	global_store_dwordx4 v[4:5], v[14:17], off offset:-2048 sc0 sc1
	global_store_dwordx4 v[4:5], v[18:21], off offset:-1024 sc0 sc1
	global_store_dwordx4 v[4:5], v[32:35], off sc0 sc1
	global_store_dwordx4 v[4:5], v[36:39], off offset:1024 sc0 sc1
	global_store_dwordx4 v[4:5], v[40:43], off offset:2048 sc0 sc1
	global_store_dwordx4 v[4:5], v[44:47], off offset:3072 sc0 sc1
	v_lshl_add_u64 v[4:5], v[4:5], 0, s[6:7]
	s_andn2_b64 exec, exec, s[8:9]
	s_cbranch_execnz .LBB0_1021
